# merged K-loop waits plus the trickle fast path in in-proj A combined; on top of v100
# baseline (speedup 1.0000x reference)
; #define PG8_STAGE(bufoff, gbase, voff) do { _Pragma("unroll") for (int _i = 0; _i < 2; ++_i) \
;         __builtin_amdgcn_global_load_lds((const unsigned*)((const char*)(gbase) + (voff)[_i]), (PG8_LAS unsigned*)(lds + (bufoff) + ldsw + _i * 8192), 16, 0, 0); } while (0)
; #define PG8_LDA(dst, b, h) do { _Pragma("unroll") for (int m = 0; m < 4; ++m) _Pragma("unroll") for (int k = 0; k < 2; ++k) dst[m][k] = *(const PG8_LAS bf16x8*)(lds + PG8_SA(b, h) + aoff + m * 2048 + k * 1024); } while (0)
; #define PG8_WAIT_V(n) asm volatile("s_waitcnt vmcnt(" #n ")" ::: "memory")
; #define PG8_WAIT_L(n) asm volatile("s_waitcnt lgkmcnt(" #n ")" ::: "memory")
; #define PG8_BAR __builtin_amdgcn_s_barrier()
; #define PG8_SCHED __builtin_amdgcn_sched_barrier(0)
;     ...
;             PG8_WAIT_V(8); PG8_WAIT_L(0); PG8_BAR; PG8_MMA(0, 0, At, B0); PG8_MMA(0, 1, At, B1); PG8_BAR; PG8_SCHED;
;             PG8_LDA(At, 0, 1); PG8_STAGE(PG8_SB(0, 0), b2, voffB); PG8_STAGE(PG8_SB(0, 1), b2 + hstepB, voffB); PG8_STAGE(PG8_SA(0, 0), a2, voffA);
;             PG8_WAIT_V(8); PG8_WAIT_L(0); PG8_BAR; PG8_MMA(1, 0, At, B0); PG8_MMA(1, 1, At, B1); PG8_BAR; PG8_SCHED;
.Lpka_da:
	s_barrier
	v_mfma_f32_16x16x32_bf16 v[132:135], v[144:147], v[210:213], v[132:135]
	v_mfma_f32_16x16x32_bf16 v[128:131], v[152:155], v[210:213], v[128:131]
	v_mfma_f32_16x16x32_bf16 v[116:119], v[144:147], v[218:221], v[116:119]
	v_mfma_f32_16x16x32_bf16 v[112:115], v[152:155], v[218:221], v[112:115]
	v_mfma_f32_16x16x32_bf16 v[100:103], v[144:147], v[226:229], v[100:103]
	v_mfma_f32_16x16x32_bf16 v[96:99], v[152:155], v[226:229], v[96:99]
	v_mfma_f32_16x16x32_bf16 v[84:87], v[144:147], v[234:237], v[84:87]
	v_mfma_f32_16x16x32_bf16 v[80:83], v[152:155], v[234:237], v[80:83]
	v_mfma_f32_16x16x32_bf16 v[132:135], v[148:151], v[214:217], v[132:135]
	v_mfma_f32_16x16x32_bf16 v[128:131], v[156:159], v[214:217], v[128:131]
	v_mfma_f32_16x16x32_bf16 v[116:119], v[148:151], v[222:225], v[116:119]
	v_mfma_f32_16x16x32_bf16 v[112:115], v[156:159], v[222:225], v[112:115]
	v_mfma_f32_16x16x32_bf16 v[100:103], v[148:151], v[230:233], v[100:103]
	v_mfma_f32_16x16x32_bf16 v[96:99], v[156:159], v[230:233], v[96:99]
	v_mfma_f32_16x16x32_bf16 v[84:87], v[148:151], v[238:241], v[84:87]
	v_mfma_f32_16x16x32_bf16 v[80:83], v[156:159], v[238:241], v[80:83]
	v_mfma_f32_16x16x32_bf16 v[140:143], v[186:189], v[210:213], v[140:143]
	v_mfma_f32_16x16x32_bf16 v[136:139], v[202:205], v[210:213], v[136:139]
	v_mfma_f32_16x16x32_bf16 v[124:127], v[186:189], v[218:221], v[124:127]
	v_mfma_f32_16x16x32_bf16 v[120:123], v[202:205], v[218:221], v[120:123]
	v_mfma_f32_16x16x32_bf16 v[108:111], v[186:189], v[226:229], v[108:111]
	v_mfma_f32_16x16x32_bf16 v[104:107], v[202:205], v[226:229], v[104:107]
	v_mfma_f32_16x16x32_bf16 v[92:95], v[186:189], v[234:237], v[92:95]
	v_mfma_f32_16x16x32_bf16 v[88:91], v[202:205], v[234:237], v[88:91]
	v_mfma_f32_16x16x32_bf16 v[140:143], v[198:201], v[214:217], v[140:143]
	v_mfma_f32_16x16x32_bf16 v[136:139], v[206:209], v[214:217], v[136:139]
	v_mfma_f32_16x16x32_bf16 v[124:127], v[198:201], v[222:225], v[124:127]
	v_mfma_f32_16x16x32_bf16 v[120:123], v[206:209], v[222:225], v[120:123]
	v_mfma_f32_16x16x32_bf16 v[108:111], v[198:201], v[230:233], v[108:111]
	v_mfma_f32_16x16x32_bf16 v[104:107], v[206:209], v[230:233], v[104:107]
	v_mfma_f32_16x16x32_bf16 v[92:95], v[198:201], v[238:241], v[92:95]
	v_mfma_f32_16x16x32_bf16 v[88:91], v[206:209], v[238:241], v[88:91]
	s_barrier
	s_add_i32 s82, s82, s15
	s_mov_b32 m0, s82
	ds_read_b128 v[210:213], v197 offset:16384
	ds_read_b128 v[214:217], v197 offset:17408
	ds_read_b128 v[218:221], v197 offset:18432
	ds_read_b128 v[222:225], v197 offset:19456
	ds_read_b128 v[226:229], v197 offset:20480
	ds_read_b128 v[230:233], v197 offset:21504
	ds_read_b128 v[234:237], v197 offset:22528
	ds_read_b128 v[238:241], v197 offset:23552
	global_load_lds_dwordx4 v170, s[72:73]
	s_add_i32 m0, s82, 0x2000
	s_add_u32 s82, s72, 0x10000
	s_addc_u32 s83, s73, 0
	s_add_i32 s86, s86, s15
	global_load_lds_dwordx4 v166, s[72:73]
	s_mov_b32 m0, s86
	s_nop 0
	global_load_lds_dwordx4 v170, s[82:83]
	s_add_i32 m0, s86, 0x2000
	s_nop 0
	global_load_lds_dwordx4 v166, s[82:83]
	s_mov_b32 m0, s63
	s_nop 0
	global_load_lds_dwordx4 v172, s[76:77]
	s_mov_b32 m0, s64
	s_nop 0
	global_load_lds_dwordx4 v168, s[76:77]
	s_cmp_eq_u64 s[100:101], 0
	s_cbranch_scc1 .Lpka_w8b
	s_lshl_b32 s100, s100, 1
	s_and_b32 s100, s100, 6
	s_bcnt1_i32_b32 vcc_lo, s100
	s_cmp_eq_u32 vcc_lo, 0
	s_cbranch_scc1 .Lpka_w8b
	s_cmp_eq_u32 vcc_lo, 1
	s_cbranch_scc1 .Lpka_w9b
	s_waitcnt vmcnt(10) lgkmcnt(0)
	s_branch .Lpka_db

; __device__ __forceinline__ void st16_wt(void* p, u32x4 v) { if (WT_STORES) asm volatile("global_store_dwordx4 %0, %1, off sc1\n\ts_nop 1" :: "v"(p), "v"(v) : "memory"); else *(u32x4*)p = v; }
; __device__ __forceinline__ unsigned cvt_pk_bf16(float lo, float hi) { unsigned r; asm volatile("v_cvt_pk_bf16_f32 %0, %1, %2" : "=v"(r) : "v"(lo), "v"(hi)); return r; }
; #define PG8_STAGE(bufoff, gbase, voff) do { _Pragma("unroll") for (int _i = 0; _i < 2; ++_i) \
;         __builtin_amdgcn_global_load_lds((const unsigned*)((const char*)(gbase) + (voff)[_i]), (PG8_LAS unsigned*)(lds + (bufoff) + ldsw + _i * 8192), 16, 0, 0); } while (0)
; #define PG8_LDA(dst, b, h) do { _Pragma("unroll") for (int m = 0; m < 4; ++m) _Pragma("unroll") for (int k = 0; k < 2; ++k) dst[m][k] = *(const PG8_LAS bf16x8*)(lds + PG8_SA(b, h) + aoff + m * 2048 + k * 1024); } while (0)
; #define PG8_LDB(dst, b, h) do { _Pragma("unroll") for (int n = 0; n < 2; ++n) _Pragma("unroll") for (int k = 0; k < 2; ++k) dst[n][k] = *(const PG8_LAS bf16x8*)(lds + PG8_SB(b, h) + boff + n * 2048 + k * 1024); } while (0)
; #define PG8_WAIT_V(n) asm volatile("s_waitcnt vmcnt(" #n ")" ::: "memory")
; #define PG8_WAIT_L(n) asm volatile("s_waitcnt lgkmcnt(" #n ")" ::: "memory")
; #define PG8_BAR __builtin_amdgcn_s_barrier()
; #define PG8_SCHED __builtin_amdgcn_sched_barrier(0)
;     __device__ __forceinline__ void operator()(const f32x4 (&acc)[2][2][4][2], const Unit& u, int wr, int wc, int fr, int fq, const bool reuse, PG8_LAS float* rscr, PG8_LAS const float* gains) const {
;     ...
;                 bf16_t* p = p0 + (size_t)(8 * ai + m) * step16;
; #pragma unroll
;                 for (int bj = 0; bj < 2; ++bj) { u32x4 w; w.x = cvt_pk_bf16(v[bj][0][0], v[bj][0][1]); w.y = cvt_pk_bf16(v[bj][0][2], v[bj][0][3]); w.z = cvt_pk_bf16(v[bj][1][0], v[bj][1][1]); w.w = cvt_pk_bf16(v[bj][1][2], v[bj][1][3]);
;                     st16_wt(p + 32 * bj, w); }
;     ...
;             PG8_WAIT_V(8); PG8_WAIT_L(0); PG8_BAR; PG8_MMA(1, 0, At, B0); PG8_MMA(1, 1, At, B1); PG8_BAR; PG8_SCHED;
;             PG8_LDB(B0, 1, 0); PG8_LDB(B1, 1, 1); PG8_SCHED; PG8_LDA(At, 1, 0); PG8_STAGE(PG8_SA(0, 1), a2 + hstep, voffA);
.Lpka_db:
	s_barrier
	v_mfma_f32_16x16x32_bf16 v[68:71], v[144:147], v[210:213], v[68:71]
	v_mfma_f32_16x16x32_bf16 v[64:67], v[152:155], v[210:213], v[64:67]
	v_mfma_f32_16x16x32_bf16 v[52:55], v[144:147], v[218:221], v[52:55]
	v_mfma_f32_16x16x32_bf16 v[48:51], v[152:155], v[218:221], v[48:51]
	v_mfma_f32_16x16x32_bf16 v[36:39], v[144:147], v[226:229], v[36:39]
	v_mfma_f32_16x16x32_bf16 v[32:35], v[152:155], v[226:229], v[32:35]
	v_mfma_f32_16x16x32_bf16 v[20:23], v[144:147], v[234:237], v[20:23]
	v_mfma_f32_16x16x32_bf16 v[16:19], v[152:155], v[234:237], v[16:19]
	v_mfma_f32_16x16x32_bf16 v[68:71], v[148:151], v[214:217], v[68:71]
	v_mfma_f32_16x16x32_bf16 v[64:67], v[156:159], v[214:217], v[64:67]
	v_mfma_f32_16x16x32_bf16 v[52:55], v[148:151], v[222:225], v[52:55]
	v_mfma_f32_16x16x32_bf16 v[48:51], v[156:159], v[222:225], v[48:51]
	v_mfma_f32_16x16x32_bf16 v[36:39], v[148:151], v[230:233], v[36:39]
	v_mfma_f32_16x16x32_bf16 v[32:35], v[156:159], v[230:233], v[32:35]
	v_mfma_f32_16x16x32_bf16 v[20:23], v[148:151], v[238:241], v[20:23]
	v_mfma_f32_16x16x32_bf16 v[16:19], v[156:159], v[238:241], v[16:19]
	v_mfma_f32_16x16x32_bf16 v[76:79], v[186:189], v[210:213], v[76:79]
	v_mfma_f32_16x16x32_bf16 v[72:75], v[202:205], v[210:213], v[72:75]
	v_mfma_f32_16x16x32_bf16 v[60:63], v[186:189], v[218:221], v[60:63]
	v_mfma_f32_16x16x32_bf16 v[56:59], v[202:205], v[218:221], v[56:59]
	v_mfma_f32_16x16x32_bf16 v[44:47], v[186:189], v[226:229], v[44:47]
	v_mfma_f32_16x16x32_bf16 v[40:43], v[202:205], v[226:229], v[40:43]
	v_mfma_f32_16x16x32_bf16 v[24:27], v[186:189], v[234:237], v[24:27]
	v_mfma_f32_16x16x32_bf16 v[28:31], v[202:205], v[234:237], v[28:31]
	v_mfma_f32_16x16x32_bf16 v[76:79], v[198:201], v[214:217], v[76:79]
	v_mfma_f32_16x16x32_bf16 v[72:75], v[206:209], v[214:217], v[72:75]
	v_mfma_f32_16x16x32_bf16 v[60:63], v[198:201], v[222:225], v[60:63]
	v_mfma_f32_16x16x32_bf16 v[56:59], v[206:209], v[222:225], v[56:59]
	v_mfma_f32_16x16x32_bf16 v[44:47], v[198:201], v[230:233], v[44:47]
	v_mfma_f32_16x16x32_bf16 v[40:43], v[206:209], v[230:233], v[40:43]
	v_mfma_f32_16x16x32_bf16 v[24:27], v[198:201], v[238:241], v[24:27]
	v_mfma_f32_16x16x32_bf16 v[28:31], v[206:209], v[238:241], v[28:31]
	s_barrier
	s_add_i32 s82, 0, 0x18000
	s_add_i32 s83, 0, 0x1c000
	v_add_u32_e32 v156, s82, v195
	v_add_u32_e32 v183, s83, v195
	ds_read_b128 v[144:147], v156
	ds_read_b128 v[148:151], v156 offset:1024
	ds_read_b128 v[152:155], v156 offset:2048
	ds_read_b128 v[156:159], v156 offset:3072
	ds_read_b128 v[186:189], v183
	ds_read_b128 v[198:201], v183 offset:1024
	ds_read_b128 v[202:205], v183 offset:2048
	ds_read_b128 v[206:209], v183 offset:3072
	s_add_u32 s76, s76, 0x40000
	s_addc_u32 s77, s77, 0
	s_mov_b32 m0, s65
	ds_read_b128 v[210:213], v197 offset:32768
	ds_read_b128 v[214:217], v197 offset:33792
	ds_read_b128 v[218:221], v197 offset:34816
	ds_read_b128 v[222:225], v197 offset:35840
	ds_read_b128 v[226:229], v197 offset:36864
	ds_read_b128 v[230:233], v197 offset:37888
	ds_read_b128 v[234:237], v197 offset:38912
	ds_read_b128 v[238:241], v197 offset:39936
	global_load_lds_dwordx4 v172, s[76:77]
	s_mov_b32 m0, s66
	s_nop 0
	global_load_lds_dwordx4 v168, s[76:77]
	s_cmp_eq_u64 s[100:101], 0
	s_cbranch_scc1 .Lpka_w8c
	s_lshl_b32 s100, s100, 1
	s_and_b32 s100, s100, 6
	s_cmp_eq_u32 s101, 0
	s_cbranch_scc1 .Lpka_nc
	s_cmp_lt_i32 s81, 2
	s_cbranch_scc1 .Lpka_nc
	s_or_b32 s100, s100, 1
	s_cmp_eq_u32 s101, 8
	s_cbranch_scc1 .Lpka_s0c
	s_cmp_eq_u32 s101, 7
	s_cbranch_scc1 .Lpka_s1c
	s_cmp_eq_u32 s101, 6
	s_cbranch_scc1 .Lpka_s2c
	s_cmp_eq_u32 s101, 5
	s_cbranch_scc1 .Lpka_s3c
	s_cmp_eq_u32 s101, 4
	s_cbranch_scc1 .Lpka_s4c
	s_cmp_eq_u32 s101, 3
	s_cbranch_scc1 .Lpka_s5c
	s_cmp_eq_u32 s101, 2
	s_cbranch_scc1 .Lpka_s6c
	global_store_dwordx4 v[254:255], v[12:15], off offset:64
	s_branch .Lpka_ic

; #define PG8_STAGE(bufoff, gbase, voff) do { _Pragma("unroll") for (int _i = 0; _i < 2; ++_i) \
;         __builtin_amdgcn_global_load_lds((const unsigned*)((const char*)(gbase) + (voff)[_i]), (PG8_LAS unsigned*)(lds + (bufoff) + ldsw + _i * 8192), 16, 0, 0); } while (0)
; #define PG8_LDA(dst, b, h) do { _Pragma("unroll") for (int m = 0; m < 4; ++m) _Pragma("unroll") for (int k = 0; k < 2; ++k) dst[m][k] = *(const PG8_LAS bf16x8*)(lds + PG8_SA(b, h) + aoff + m * 2048 + k * 1024); } while (0)
; #define PG8_WAIT_V(n) asm volatile("s_waitcnt vmcnt(" #n ")" ::: "memory")
; #define PG8_WAIT_L(n) asm volatile("s_waitcnt lgkmcnt(" #n ")" ::: "memory")
; #define PG8_BAR __builtin_amdgcn_s_barrier()
; #define PG8_SCHED __builtin_amdgcn_sched_barrier(0)
;     ...
;             PG8_WAIT_V(8); PG8_WAIT_L(0); PG8_BAR; PG8_MMA(0, 0, At, B0); PG8_MMA(0, 1, At, B1); PG8_BAR; PG8_SCHED;
;             PG8_LDA(At, 1, 1); PG8_STAGE(PG8_SB(1, 0), b3, voffB); PG8_STAGE(PG8_SB(1, 1), b3 + hstepB, voffB); PG8_STAGE(PG8_SA(1, 0), a3, voffA);
;             PG8_WAIT_V(8); PG8_WAIT_L(0); PG8_BAR; PG8_MMA(1, 0, At, B0); PG8_MMA(1, 1, At, B1); PG8_BAR; PG8_SCHED;
.Lpka_dc:
	s_barrier
	v_mfma_f32_16x16x32_bf16 v[132:135], v[144:147], v[210:213], v[132:135]
	v_mfma_f32_16x16x32_bf16 v[128:131], v[152:155], v[210:213], v[128:131]
	v_mfma_f32_16x16x32_bf16 v[116:119], v[144:147], v[218:221], v[116:119]
	v_mfma_f32_16x16x32_bf16 v[112:115], v[152:155], v[218:221], v[112:115]
	v_mfma_f32_16x16x32_bf16 v[100:103], v[144:147], v[226:229], v[100:103]
	v_mfma_f32_16x16x32_bf16 v[96:99], v[152:155], v[226:229], v[96:99]
	v_mfma_f32_16x16x32_bf16 v[84:87], v[144:147], v[234:237], v[84:87]
	v_mfma_f32_16x16x32_bf16 v[80:83], v[152:155], v[234:237], v[80:83]
	v_mfma_f32_16x16x32_bf16 v[132:135], v[148:151], v[214:217], v[132:135]
	v_mfma_f32_16x16x32_bf16 v[128:131], v[156:159], v[214:217], v[128:131]
	v_mfma_f32_16x16x32_bf16 v[116:119], v[148:151], v[222:225], v[116:119]
	v_mfma_f32_16x16x32_bf16 v[112:115], v[156:159], v[222:225], v[112:115]
	v_mfma_f32_16x16x32_bf16 v[100:103], v[148:151], v[230:233], v[100:103]
	v_mfma_f32_16x16x32_bf16 v[96:99], v[156:159], v[230:233], v[96:99]
	v_mfma_f32_16x16x32_bf16 v[84:87], v[148:151], v[238:241], v[84:87]
	v_mfma_f32_16x16x32_bf16 v[80:83], v[156:159], v[238:241], v[80:83]
	v_mfma_f32_16x16x32_bf16 v[140:143], v[186:189], v[210:213], v[140:143]
	v_mfma_f32_16x16x32_bf16 v[136:139], v[202:205], v[210:213], v[136:139]
	v_mfma_f32_16x16x32_bf16 v[124:127], v[186:189], v[218:221], v[124:127]
	v_mfma_f32_16x16x32_bf16 v[120:123], v[202:205], v[218:221], v[120:123]
	v_mfma_f32_16x16x32_bf16 v[108:111], v[186:189], v[226:229], v[108:111]
	v_mfma_f32_16x16x32_bf16 v[104:107], v[202:205], v[226:229], v[104:107]
	v_mfma_f32_16x16x32_bf16 v[92:95], v[186:189], v[234:237], v[92:95]
	v_mfma_f32_16x16x32_bf16 v[88:91], v[202:205], v[234:237], v[88:91]
	v_mfma_f32_16x16x32_bf16 v[140:143], v[198:201], v[214:217], v[140:143]
	v_mfma_f32_16x16x32_bf16 v[136:139], v[206:209], v[214:217], v[136:139]
	v_mfma_f32_16x16x32_bf16 v[124:127], v[198:201], v[222:225], v[124:127]
	v_mfma_f32_16x16x32_bf16 v[120:123], v[206:209], v[222:225], v[120:123]
	v_mfma_f32_16x16x32_bf16 v[108:111], v[198:201], v[230:233], v[108:111]
	v_mfma_f32_16x16x32_bf16 v[104:107], v[206:209], v[230:233], v[104:107]
	v_mfma_f32_16x16x32_bf16 v[92:95], v[198:201], v[238:241], v[92:95]
	v_mfma_f32_16x16x32_bf16 v[88:91], v[206:209], v[238:241], v[88:91]
	s_barrier
	s_add_i32 m0, s82, s15
	s_add_u32 vcc_lo, s72, 0x80
	s_addc_u32 vcc_hi, s73, 0
	ds_read_b128 v[210:213], v197 offset:49152
	ds_read_b128 v[214:217], v197 offset:50176
	ds_read_b128 v[218:221], v197 offset:51200
	ds_read_b128 v[222:225], v197 offset:52224
	ds_read_b128 v[226:229], v197 offset:53248
	ds_read_b128 v[230:233], v197 offset:54272
	ds_read_b128 v[234:237], v197 offset:55296
	ds_read_b128 v[238:241], v197 offset:56320
	global_load_lds_dwordx4 v170, vcc
	s_add_i32 m0, m0, 0x2000
	s_nop 0
	global_load_lds_dwordx4 v166, vcc
	s_add_u32 s72, s72, 0x10080
	s_addc_u32 s73, s73, 0
	s_add_i32 m0, s83, s15
	s_nop 0
	global_load_lds_dwordx4 v170, s[72:73]
	s_add_i32 m0, m0, 0x2000
	s_nop 0
	global_load_lds_dwordx4 v166, s[72:73]
	s_add_u32 vcc_lo, s76, 0xfffc0080
	s_addc_u32 vcc_hi, s77, -1
	s_mov_b32 m0, s74
	s_nop 0
	global_load_lds_dwordx4 v172, vcc
	s_mov_b32 m0, s75
	s_nop 0
	global_load_lds_dwordx4 v168, vcc
	s_cmp_eq_u64 s[100:101], 0
	s_cbranch_scc1 .Lpka_w8e
	s_lshl_b32 s100, s100, 1
	s_and_b32 s100, s100, 6
	s_bcnt1_i32_b32 vcc_lo, s100
	s_cmp_eq_u32 vcc_lo, 0
	s_cbranch_scc1 .Lpka_w8e
	s_cmp_eq_u32 vcc_lo, 1
	s_cbranch_scc1 .Lpka_w9e
	s_waitcnt vmcnt(10) lgkmcnt(0)
	s_branch .Lpka_de

; #define PG8_WAIT_V(n) asm volatile("s_waitcnt vmcnt(" #n ")" ::: "memory")
; #define PG8_WAIT_L(n) asm volatile("s_waitcnt lgkmcnt(" #n ")" ::: "memory")
; #define PG8_BAR __builtin_amdgcn_s_barrier()
; #define PG8_SCHED __builtin_amdgcn_sched_barrier(0)
;     ...
;             PG8_WAIT_V(8); PG8_WAIT_L(0); PG8_BAR; PG8_MMA(1, 0, At, B0); PG8_MMA(1, 1, At, B1); PG8_BAR; PG8_SCHED;
;         }
;         if constexpr (ALIGN_EPI) { if (wr == 0) PG8_BAR; }
.Lpka_de:
	s_barrier
	v_mfma_f32_16x16x32_bf16 v[68:71], v[144:147], v[210:213], v[68:71]
	v_mfma_f32_16x16x32_bf16 v[64:67], v[152:155], v[210:213], v[64:67]
	v_mfma_f32_16x16x32_bf16 v[52:55], v[144:147], v[218:221], v[52:55]
	v_mfma_f32_16x16x32_bf16 v[48:51], v[152:155], v[218:221], v[48:51]
	v_mfma_f32_16x16x32_bf16 v[36:39], v[144:147], v[226:229], v[36:39]
	v_mfma_f32_16x16x32_bf16 v[32:35], v[152:155], v[226:229], v[32:35]
	v_mfma_f32_16x16x32_bf16 v[20:23], v[144:147], v[234:237], v[20:23]
	v_mfma_f32_16x16x32_bf16 v[16:19], v[152:155], v[234:237], v[16:19]
	v_mfma_f32_16x16x32_bf16 v[68:71], v[148:151], v[214:217], v[68:71]
	v_mfma_f32_16x16x32_bf16 v[64:67], v[156:159], v[214:217], v[64:67]
	v_mfma_f32_16x16x32_bf16 v[52:55], v[148:151], v[222:225], v[52:55]
	v_mfma_f32_16x16x32_bf16 v[48:51], v[156:159], v[222:225], v[48:51]
	v_mfma_f32_16x16x32_bf16 v[36:39], v[148:151], v[230:233], v[36:39]
	v_mfma_f32_16x16x32_bf16 v[32:35], v[156:159], v[230:233], v[32:35]
	v_mfma_f32_16x16x32_bf16 v[20:23], v[148:151], v[238:241], v[20:23]
	v_mfma_f32_16x16x32_bf16 v[16:19], v[156:159], v[238:241], v[16:19]
	v_mfma_f32_16x16x32_bf16 v[76:79], v[186:189], v[210:213], v[76:79]
	v_mfma_f32_16x16x32_bf16 v[72:75], v[202:205], v[210:213], v[72:75]
	v_mfma_f32_16x16x32_bf16 v[60:63], v[186:189], v[218:221], v[60:63]
	v_mfma_f32_16x16x32_bf16 v[56:59], v[202:205], v[218:221], v[56:59]
	v_mfma_f32_16x16x32_bf16 v[44:47], v[186:189], v[226:229], v[44:47]
	v_mfma_f32_16x16x32_bf16 v[40:43], v[202:205], v[226:229], v[40:43]
	v_mfma_f32_16x16x32_bf16 v[24:27], v[186:189], v[234:237], v[24:27]
	v_mfma_f32_16x16x32_bf16 v[28:31], v[202:205], v[234:237], v[28:31]
	v_mfma_f32_16x16x32_bf16 v[76:79], v[198:201], v[214:217], v[76:79]
	v_mfma_f32_16x16x32_bf16 v[72:75], v[206:209], v[214:217], v[72:75]
	v_mfma_f32_16x16x32_bf16 v[60:63], v[198:201], v[222:225], v[60:63]
	v_mfma_f32_16x16x32_bf16 v[56:59], v[206:209], v[222:225], v[56:59]
	v_mfma_f32_16x16x32_bf16 v[44:47], v[198:201], v[230:233], v[44:47]
	v_mfma_f32_16x16x32_bf16 v[40:43], v[206:209], v[230:233], v[40:43]
	v_mfma_f32_16x16x32_bf16 v[24:27], v[198:201], v[238:241], v[24:27]
	v_mfma_f32_16x16x32_bf16 v[28:31], v[206:209], v[238:241], v[28:31]
	s_barrier
	s_add_i32 s81, s81, 2
	s_cmp_eq_u32 s81, 2
	s_cselect_b32 s101, s32, s101
	s_add_u32 s38, s38, 0x100
	s_addc_u32 s39, s39, 0
	s_add_u32 s61, s61, 0x100
	s_addc_u32 s80, s80, 0
	s_cmp_gt_u32 s81, 13
	s_cbranch_scc0 .LBB0_206
	v_mov_b32_e32 v162, 0x500
	v_mov_b32_e32 v163, 0
	v_mov_b32_e32 v164, 0x4ff
	v_mov_b32_e32 v165, 0
	v_mov_b32_e32 v190, 0x358637bd
	v_mov_b32_e32 v191, 1
	v_mov_b32_e32 v192, 0x300
	v_mov_b32_e32 v193, 0x200
	s_and_b64 vcc, exec, s[22:23]
	s_cbranch_vccz .LBB0_209
	s_barrier
